# hgrn_load prefix-sum phases 3/4/5: hoist all LDS reads ahead of one wait (h1+h3 copies), b128 vector reads/writes in phase 5
# speedup vs baseline: 1.0058x; 1.0036x over previous
; template <bool WANT_Q>
; DI void hgrn_load(const Params& p, int l, int bh, int c, float* QS, float* B2, float* LK, float* V, float* lbv) {
;     ...
;     float off = 0.f;
;     for (int sg = 0; sg < seg; ++sg) off += B2[(sg * 16 + 15) * HP + d];
;     __syncthreads();
; #pragma unroll
;     for (int i = 0; i < 16; ++i) { const int tt = seg * 16 + i; B2[tt * HP + d] += off; }
;   }
;   __syncthreads();
; #pragma unroll
;   for (int j = 0; j < 16; ++j) LK[t * HP + d0 + j] -= B2[t * HP + d0 + j];
;   __syncthreads();
.LBB0_617:
	s_or_b64 exec, exec, s[2:3]
	s_barrier
	ds_read2_b32 v[140:141], v5 offset1:68
	ds_read2_b32 v[142:143], v5 offset0:136 offset1:204
	ds_read2_b32 v[144:145], v4 offset0:16 offset1:84
	ds_read2_b32 v[146:147], v4 offset0:152 offset1:220
	ds_read2_b32 v[148:149], v3 offset0:32 offset1:100
	ds_read2_b32 v[150:151], v3 offset0:168 offset1:236
	ds_read2_b32 v[152:153], v2 offset0:48 offset1:116
	ds_read2_b32 v[154:155], v2 offset0:184 offset1:252
	v_bfe_u32 v33, v32, 2, 6
	v_and_b32_e32 v27, 3, v32
	s_movk_i32 s2, 0x110
	s_mov_b32 s5, 0
	v_mov_b32_e32 v28, v1
	v_mov_b32_e32 v29, v1
	v_mov_b32_e32 v10, v1
	v_mov_b32_e32 v11, v1
	v_mov_b32_e32 v13, v1
	s_waitcnt lgkmcnt(0)
	v_add_f32_e32 v76, v15, v140
	v_add_f32_e32 v77, v15, v141
	ds_write2_b32 v5, v76, v77 offset1:68
	v_add_f32_e32 v78, v15, v142
	v_add_f32_e32 v79, v15, v143
	ds_write2_b32 v5, v78, v79 offset0:136 offset1:204
	v_add_f32_e32 v80, v15, v144
	v_add_f32_e32 v81, v15, v145
	ds_write2_b32 v4, v80, v81 offset0:16 offset1:84
	v_add_f32_e32 v82, v15, v146
	v_add_f32_e32 v83, v15, v147
	ds_write2_b32 v4, v82, v83 offset0:152 offset1:220
	v_add_f32_e32 v84, v15, v148
	v_add_f32_e32 v85, v15, v149
	ds_write2_b32 v3, v84, v85 offset0:32 offset1:100
	v_add_f32_e32 v86, v15, v150
	v_add_f32_e32 v87, v15, v151
	ds_write2_b32 v3, v86, v87 offset0:168 offset1:236
	v_add_f32_e32 v88, v15, v152
	v_add_f32_e32 v89, v15, v153
	ds_write2_b32 v2, v88, v89 offset0:48 offset1:116
	v_add_f32_e32 v90, v15, v154
	v_add_f32_e32 v91, v15, v155
	ds_write2_b32 v2, v90, v91 offset0:184 offset1:252
	s_waitcnt lgkmcnt(0)
	s_barrier
	ds_read_b128 v[2:5], v12 offset:17408
	ds_read_b128 v[6:9], v12 offset:17424
	ds_read_b128 v[14:17], v12 offset:17440
	ds_read_b128 v[18:21], v12 offset:17456
	ds_read_b128 v[34:37], v12 offset:34816
	ds_read_b128 v[140:143], v12 offset:34832
	ds_read_b128 v[144:147], v12 offset:34848
	ds_read_b128 v[148:151], v12 offset:34864
	s_waitcnt lgkmcnt(0)
	v_pk_add_f32 v[2:3], v[34:35], v[2:3] neg_lo:[0,1] neg_hi:[0,1]
	v_pk_add_f32 v[4:5], v[36:37], v[4:5] neg_lo:[0,1] neg_hi:[0,1]
	ds_write_b128 v12, v[2:5] offset:34816
	v_mad_u32_u24 v35, v27, s2, v46
	v_pk_add_f32 v[140:141], v[140:141], v[6:7] neg_lo:[0,1] neg_hi:[0,1]
	v_pk_add_f32 v[142:143], v[142:143], v[8:9] neg_lo:[0,1] neg_hi:[0,1]
	ds_write_b128 v12, v[140:143] offset:34832
	v_mov_b32_e32 v6, v1
	v_mov_b32_e32 v7, v1
	v_mov_b32_e32 v8, v1
	v_mov_b32_e32 v9, v1
	v_pk_add_f32 v[144:145], v[144:145], v[14:15] neg_lo:[0,1] neg_hi:[0,1]
	v_pk_add_f32 v[146:147], v[146:147], v[16:17] neg_lo:[0,1] neg_hi:[0,1]
	ds_write_b128 v12, v[144:147] offset:34848
	v_mov_b32_e32 v14, v1
	v_mov_b32_e32 v15, v1
	v_pk_add_f32 v[148:149], v[148:149], v[18:19] neg_lo:[0,1] neg_hi:[0,1]
	v_pk_add_f32 v[150:151], v[150:151], v[20:21] neg_lo:[0,1] neg_hi:[0,1]
	ds_write_b128 v12, v[148:151] offset:34864
	v_lshrrev_b32_e32 v2, 4, v32
	v_and_b32_e32 v2, 12, v2
	v_mul_u32_u24_e32 v3, 0x44, v33
	v_lshl_add_u32 v34, v3, 2, v250
	v_cmp_ne_u32_e32 vcc, 0, v2
	v_cmp_lt_u32_e64 s[0:1], 7, v2
	v_cmp_lt_u32_e64 s[44:45], 5, v2
	v_cmp_lt_u32_e64 s[46:47], 6, v2
	v_cmp_eq_u32_e64 s[48:49], 12, v2
	v_cmp_lt_u32_e64 s[50:51], 9, v2
	v_cmp_lt_u32_e64 s[52:53], 10, v2
	v_mov_b32_e32 v2, v1
	v_mov_b32_e32 v3, v1
	v_mov_b32_e32 v4, v1
	v_mov_b32_e32 v5, v1
	v_mov_b32_e32 v12, v1
	s_waitcnt lgkmcnt(0)
	s_barrier
	s_branch .LBB0_619

; __device__ __forceinline__ int opaque_tid() { int t = threadIdx.x; asm volatile("" : "+v"(t)); return t; }
; DI float ex2(float x) { return __builtin_amdgcn_exp2f(x); }
; template <bool WANT_Q>
; DI void hgrn_load(const Params& p, int l, int bh, int c, float* QS, float* B2, float* LK, float* V, float* lbv) {
;     ...
;     float off = 0.f;
;     for (int sg = 0; sg < seg; ++sg) off += B2[(sg * 16 + 15) * HP + d];
;     __syncthreads();
; #pragma unroll
;     for (int i = 0; i < 16; ++i) { const int tt = seg * 16 + i; B2[tt * HP + d] += off; }
;   }
;   __syncthreads();
; #pragma unroll
;   for (int j = 0; j < 16; ++j) LK[t * HP + d0 + j] -= B2[t * HP + d0 + j];
;   __syncthreads();
; }
; DI void hgrn_h1(const Params& p, int l, int item, char* lds) {
;   float* QS = (float*)lds; float* B2 = QS + 64 * HP; float* LK = B2 + 64 * HP; float* V = LK + 64 * HP; float* lbv = V + 64 * HP;
;   const int tid = opaque_tid() & 255, bh = item >> 6, c = item & 63;
;   hgrn_load<false>(p, l, bh, c, QS, B2, LK, V, lbv);
;   { const int t = tid >> 2, d0 = (tid & 3) * 16;
; #pragma unroll
;     for (int j = 0; j < 16; ++j) QS[t * HP + d0 + j] = ex2(LK[t * HP + d0 + j] + B2[63 * HP + d0 + j]); }
;   if (tid < 64) p.G[(size_t)item * 64 + tid] = ex2(B2[63 * HP + tid]);
.LBB0_825:
	s_or_b64 exec, exec, s[2:3]
	s_barrier
	ds_read2_b32 v[64:65], v6 offset1:68
	ds_read2_b32 v[66:67], v6 offset0:136 offset1:204
	ds_read2_b32 v[68:69], v5 offset0:16 offset1:84
	ds_read2_b32 v[70:71], v5 offset0:152 offset1:220
	ds_read2_b32 v[72:73], v4 offset0:32 offset1:100
	ds_read2_b32 v[74:75], v4 offset0:168 offset1:236
	ds_read2_b32 v[76:77], v3 offset0:48 offset1:116
	ds_read2_b32 v[78:79], v3 offset0:184 offset1:252
	s_movk_i32 s2, 0x44
	v_cmp_lt_u32_sdwa s[4:5], v23, v251 src0_sel:BYTE_0 src1_sel:DWORD
	v_ashrrev_i32_e32 v19, 31, v18
	s_waitcnt lgkmcnt(0)
	v_add_f32_e32 v80, v2, v64
	v_add_f32_e32 v81, v2, v65
	ds_write2_b32 v6, v80, v81 offset1:68
	v_add_f32_e32 v82, v2, v66
	v_add_f32_e32 v83, v2, v67
	ds_write2_b32 v6, v82, v83 offset0:136 offset1:204
	v_add_f32_e32 v84, v2, v68
	v_add_f32_e32 v85, v2, v69
	ds_write2_b32 v5, v84, v85 offset0:16 offset1:84
	v_add_f32_e32 v86, v2, v70
	v_add_f32_e32 v87, v2, v71
	ds_write2_b32 v5, v86, v87 offset0:152 offset1:220
	v_add_f32_e32 v88, v2, v72
	v_add_f32_e32 v89, v2, v73
	ds_write2_b32 v4, v88, v89 offset0:32 offset1:100
	v_add_f32_e32 v90, v2, v74
	v_add_f32_e32 v91, v2, v75
	ds_write2_b32 v4, v90, v91 offset0:168 offset1:236
	v_add_f32_e32 v92, v2, v76
	v_add_f32_e32 v93, v2, v77
	ds_write2_b32 v3, v92, v93 offset0:48 offset1:116
	v_add_f32_e32 v94, v2, v78
	v_add_f32_e32 v95, v2, v79
	ds_write2_b32 v3, v94, v95 offset0:184 offset1:252
	s_waitcnt lgkmcnt(0)
	s_barrier
	ds_read_b128 v[2:5], v0 offset:17408
	ds_read_b128 v[6:9], v0 offset:17424
	ds_read_b128 v[10:13], v0 offset:17440
	ds_read_b128 v[14:17], v0 offset:17456
	ds_read_b128 v[24:27], v0 offset:34816
	ds_read_b128 v[64:67], v0 offset:34832
	ds_read_b128 v[68:71], v0 offset:34848
	ds_read_b128 v[72:75], v0 offset:34864
	s_waitcnt lgkmcnt(0)
	v_pk_add_f32 v[2:3], v[24:25], v[2:3] neg_lo:[0,1] neg_hi:[0,1]
	v_pk_add_f32 v[4:5], v[26:27], v[4:5] neg_lo:[0,1] neg_hi:[0,1]
	ds_write_b128 v0, v[2:5] offset:34816
	v_lshlrev_b32_e32 v24, 4, v23
	v_pk_add_f32 v[64:65], v[64:65], v[6:7] neg_lo:[0,1] neg_hi:[0,1]
	v_pk_add_f32 v[66:67], v[66:67], v[8:9] neg_lo:[0,1] neg_hi:[0,1]
	ds_write_b128 v0, v[64:67] offset:34832
	v_pk_add_f32 v[68:69], v[68:69], v[10:11] neg_lo:[0,1] neg_hi:[0,1]
	v_pk_add_f32 v[70:71], v[70:71], v[12:13] neg_lo:[0,1] neg_hi:[0,1]
	ds_write_b128 v0, v[68:71] offset:34848
	v_and_b32_e32 v10, 48, v24
	v_pk_add_f32 v[72:73], v[72:73], v[14:15] neg_lo:[0,1] neg_hi:[0,1]
	v_pk_add_f32 v[74:75], v[74:75], v[16:17] neg_lo:[0,1] neg_hi:[0,1]
	ds_write_b128 v0, v[72:75] offset:34864
	v_bfe_u32 v0, v23, 2, 6
	v_mad_u32_u24 v0, v0, s2, v10
	v_lshl_add_u32 v0, v0, 2, v250
	v_lshl_add_u32 v10, v10, 2, v250
	s_waitcnt lgkmcnt(0)
	s_barrier
	ds_read_b128 v[2:5], v0 offset:34816
	ds_read_b128 v[6:9], v0 offset:34832
	ds_read_b128 v[64:67], v0 offset:34848
	ds_read_b128 v[68:71], v0 offset:34864
	ds_read_b128 v[72:75], v10 offset:34544
	ds_read_b128 v[76:79], v10 offset:34560
	ds_read_b128 v[80:83], v10 offset:34576
	ds_read_b128 v[84:87], v10 offset:34592
	s_waitcnt lgkmcnt(0)
	v_add_f32_e32 v72, v2, v72
	v_add_f32_e32 v73, v3, v73
	v_add_f32_e32 v74, v4, v74
	v_add_f32_e32 v75, v5, v75
	v_add_f32_e32 v76, v6, v76
	v_add_f32_e32 v77, v7, v77
	v_add_f32_e32 v78, v8, v78
	v_add_f32_e32 v79, v9, v79
	v_add_f32_e32 v80, v64, v80
	v_add_f32_e32 v81, v65, v81
	v_add_f32_e32 v82, v66, v82
	v_add_f32_e32 v83, v67, v83
	v_add_f32_e32 v84, v68, v84
	v_add_f32_e32 v85, v69, v85
	v_add_f32_e32 v86, v70, v86
	v_add_f32_e32 v87, v71, v87
	v_exp_f32_e32 v72, v72
	v_exp_f32_e32 v73, v73
	v_exp_f32_e32 v74, v74
	v_exp_f32_e32 v75, v75
	v_exp_f32_e32 v76, v76
	v_exp_f32_e32 v77, v77
	v_exp_f32_e32 v78, v78
	v_exp_f32_e32 v79, v79
	v_exp_f32_e32 v80, v80
	v_exp_f32_e32 v81, v81
	v_exp_f32_e32 v82, v82
	v_exp_f32_e32 v83, v83
	v_exp_f32_e32 v84, v84
	v_exp_f32_e32 v85, v85
	v_exp_f32_e32 v86, v86
	v_exp_f32_e32 v87, v87
	s_nop 1
	ds_write_b128 v0, v[72:75]
	ds_write_b128 v0, v[76:79] offset:16
	ds_write_b128 v0, v[80:83] offset:32
	ds_write_b128 v0, v[84:87] offset:48
	s_and_saveexec_b64 s[2:3], s[4:5]
	s_cbranch_execz .LBB0_827
	v_readlane_b32 s40, v253, 0
	v_lshlrev_b64 v[2:3], 8, v[18:19]
	v_readlane_b32 s42, v253, 2
	v_readlane_b32 s43, v253, 3
	v_mov_b32_e32 v0, 2
	v_lshlrev_b32_sdwa v0, v0, v23 dst_sel:DWORD dst_unused:UNUSED_PAD src0_sel:DWORD src1_sel:BYTE_0
	v_lshl_add_u64 v[2:3], s[42:43], 0, v[2:3]
	v_lshl_add_u64 v[2:3], v[2:3], 0, v[0:1]
	v_add_u32_e32 v0, v250, v0
	ds_read_b32 v0, v0 offset:34544
	v_readlane_b32 s41, v253, 1
	s_waitcnt lgkmcnt(0)
	v_exp_f32_e32 v0, v0
	global_store_dword v[2:3], v0, off
